# o30 with at most 4 filler pulls per idle workgroup in WIN's last round (the remaining ~68 gate/up pulls stay at the end of the MIX1 queue)
# baseline (speedup 1.0000x reference)
.LBB0_1169:
	s_waitcnt vmcnt(0)
	v_readlane_b32 s80, v254, 8
	v_readlane_b32 s81, v254, 9
	v_readlane_b32 s82, v254, 10
	v_readlane_b32 s83, v254, 11
	v_readlane_b32 s84, v254, 12
	v_readlane_b32 s85, v254, 13
	v_readlane_b32 s86, v254, 14
	v_readlane_b32 s87, v254, 15
	s_barrier
	v_readlane_b32 s101, v253, 0
	s_nop 3
	s_cmpk_lt_u32 s101, 0x61
	s_cbranch_scc1 .LBB0_1170
	s_mov_b32 s99, 1
	s_movk_i32 s98, 0x410
	s_movk_i32 s100, 0x5
	s_add_u32 s0, s86, 0xc800
	s_addc_u32 s1, s87, 0
	v_writelane_b32 v254, s0, 22
	v_mov_b32_e32 v1, v0
	s_branch .Lmix1_entry
